# XCD barrier followers poll with s_sleep 4 instead of 1 (less contention on the release word)
# speedup vs baseline: 1.0209x; 1.0003x over previous
; __global__ void __launch_bounds__(512, 2) mega(Params p_, int ph_lo, int ph_hi, int coop) {
;     ...
;     if (coop && ph + 1 < ph_hi) cg::this_grid().sync();
.Lgb_poll_x:
	s_sleep 4
	global_load_dword v2, v129, s[10:11] offset:2304 sc1
	s_add_u32 s14, s14, 1
	s_waitcnt vmcnt(0)
	v_cmp_gt_u32_e32 vcc, s13, v2
	s_and_b64 vcc, exec, vcc
	s_cbranch_vccz .Lgb_fol_done
	s_cmp_lt_u32 s14, 0x20000
	s_cbranch_scc1 .Lgb_poll_x
